# previous combination + GEMM group 1 (in-proj, q-up, kv-up): first iteration after an epilogue with C=0 instead of zeroing 128 accumulators
# baseline (speedup 1.0000x reference)
.LBB0_174:
	s_mov_b32 s32, 0
	s_cmp_lt_i32 s45, 2
	s_mov_b64 s[4:5], -1
	s_cbranch_scc1 .LBB0_187
	s_cmp_lt_i32 s45, 3
	s_cbranch_scc1 .LBB0_184
	s_cmp_lt_i32 s45, 4
	s_cbranch_scc1 .LBB0_181
	s_cmp_lg_u32 s45, 4
	s_mov_b64 s[0:1], -1
	s_cbranch_scc0 .LBB0_179
	s_mov_b64 s[0:1], 0

.LBB0_203:
	s_mov_b32 s32, 1
	s_andn2_b64 vcc, exec, s[4:5]
	s_mov_b32 s46, s67
	s_mov_b32 s3, s68
	s_mov_b64 s[8:9], s[34:35]
	s_mov_b64 s[6:7], s[0:1]
	s_cbranch_vccz .LBB0_315

.LBB0_210:
	s_add_u32 s6, s6, 0x80
	s_addc_u32 s7, s7, 0
	s_add_u32 s36, s8, 0x100
	v_mov_b32_e32 v2, 0
	s_addc_u32 s37, s9, 0
	s_mov_b32 s8, 0
	s_cmp_eq_u32 s32, 1
	s_cbranch_scc1 .Lg1_first
	v_mov_b32_e32 v3, v2
	v_mov_b32_e32 v4, v2
	v_mov_b32_e32 v5, v2
	v_mov_b32_e32 v6, v2
	v_mov_b32_e32 v7, v2
	v_mov_b32_e32 v8, v2
	v_mov_b32_e32 v9, v2
	v_mov_b32_e32 v18, v2
	v_mov_b32_e32 v19, v2
	v_mov_b32_e32 v20, v2
	v_mov_b32_e32 v21, v2
	v_mov_b32_e32 v22, v2
	v_mov_b32_e32 v23, v2
	v_mov_b32_e32 v24, v2
	v_mov_b32_e32 v25, v2
	v_mov_b32_e32 v34, v2
	v_mov_b32_e32 v35, v2
	v_mov_b32_e32 v36, v2
	v_mov_b32_e32 v37, v2
	v_mov_b32_e32 v38, v2
	v_mov_b32_e32 v39, v2
	v_mov_b32_e32 v40, v2
	v_mov_b32_e32 v41, v2
	v_mov_b32_e32 v50, v2
	v_mov_b32_e32 v51, v2
	v_mov_b32_e32 v52, v2
	v_mov_b32_e32 v53, v2
	v_mov_b32_e32 v54, v2
	v_mov_b32_e32 v55, v2
	v_mov_b32_e32 v56, v2
	v_mov_b32_e32 v57, v2
	v_mov_b32_e32 v10, v2
	v_mov_b32_e32 v11, v2
	v_mov_b32_e32 v12, v2
	v_mov_b32_e32 v13, v2
	v_mov_b32_e32 v14, v2
	v_mov_b32_e32 v15, v2
	v_mov_b32_e32 v16, v2
	v_mov_b32_e32 v17, v2
	v_mov_b32_e32 v26, v2
	v_mov_b32_e32 v27, v2
	v_mov_b32_e32 v28, v2
	v_mov_b32_e32 v29, v2
	v_mov_b32_e32 v30, v2
	v_mov_b32_e32 v31, v2
	v_mov_b32_e32 v32, v2
	v_mov_b32_e32 v33, v2
	v_mov_b32_e32 v42, v2
	v_mov_b32_e32 v43, v2
	v_mov_b32_e32 v44, v2
	v_mov_b32_e32 v45, v2
	v_mov_b32_e32 v46, v2
	v_mov_b32_e32 v47, v2
	v_mov_b32_e32 v48, v2
	v_mov_b32_e32 v49, v2
	v_mov_b32_e32 v58, v2
	v_mov_b32_e32 v59, v2
	v_mov_b32_e32 v60, v2
	v_mov_b32_e32 v61, v2
	v_mov_b32_e32 v62, v2
	v_mov_b32_e32 v63, v2
	v_mov_b32_e32 v64, v2
	v_mov_b32_e32 v65, v2
	v_mov_b32_e32 v66, v2
	v_mov_b32_e32 v67, v2
	v_mov_b32_e32 v68, v2
	v_mov_b32_e32 v69, v2
	v_mov_b32_e32 v70, v2
	v_mov_b32_e32 v71, v2
	v_mov_b32_e32 v72, v2
	v_mov_b32_e32 v73, v2
	v_mov_b32_e32 v82, v2
	v_mov_b32_e32 v83, v2
	v_mov_b32_e32 v84, v2
	v_mov_b32_e32 v85, v2
	v_mov_b32_e32 v86, v2
	v_mov_b32_e32 v87, v2
	v_mov_b32_e32 v88, v2
	v_mov_b32_e32 v89, v2
	v_mov_b32_e32 v98, v2
	v_mov_b32_e32 v99, v2
	v_mov_b32_e32 v100, v2
	v_mov_b32_e32 v101, v2
	v_mov_b32_e32 v102, v2
	v_mov_b32_e32 v103, v2
	v_mov_b32_e32 v104, v2
	v_mov_b32_e32 v105, v2
	v_mov_b32_e32 v114, v2
	v_mov_b32_e32 v115, v2
	v_mov_b32_e32 v116, v2
	v_mov_b32_e32 v117, v2
	v_mov_b32_e32 v118, v2
	v_mov_b32_e32 v119, v2
	v_mov_b32_e32 v120, v2
	v_mov_b32_e32 v121, v2
	v_mov_b32_e32 v74, v2
	v_mov_b32_e32 v75, v2
	v_mov_b32_e32 v76, v2
	v_mov_b32_e32 v77, v2
	v_mov_b32_e32 v78, v2
	v_mov_b32_e32 v79, v2
	v_mov_b32_e32 v80, v2
	v_mov_b32_e32 v81, v2
	v_mov_b32_e32 v90, v2
	v_mov_b32_e32 v91, v2
	v_mov_b32_e32 v92, v2
	v_mov_b32_e32 v93, v2
	v_mov_b32_e32 v94, v2
	v_mov_b32_e32 v95, v2
	v_mov_b32_e32 v96, v2
	v_mov_b32_e32 v97, v2
	v_mov_b32_e32 v106, v2
	v_mov_b32_e32 v107, v2
	v_mov_b32_e32 v108, v2
	v_mov_b32_e32 v109, v2
	v_mov_b32_e32 v110, v2
	v_mov_b32_e32 v111, v2
	v_mov_b32_e32 v112, v2
	v_mov_b32_e32 v113, v2
	v_mov_b32_e32 v122, v2
	v_mov_b32_e32 v123, v2
	v_mov_b32_e32 v124, v2
	v_mov_b32_e32 v125, v2
	v_mov_b32_e32 v126, v2
	v_mov_b32_e32 v127, v2
	v_mov_b32_e32 v128, v2
	v_mov_b32_e32 v129, v2

.Lg1_after:
	s_and_b64 vcc, exec, s[28:29]
	s_cbranch_vccnz .LBB0_215
	s_lshl_b32 s8, s3, 8
	s_cmp_lt_i32 s45, 2
	s_mov_b64 s[6:7], -1
	s_cbranch_scc0 .LBB0_216

.Lg1_first:
	s_mov_b32 s32, 0
	s_add_i32 s38, s8, 2
	s_add_u32 s39, s6, 0x80
	s_addc_u32 s9, s7, 0
	s_add_i32 s69, 0, 0x10000
	s_cmp_eq_u32 s57, s8
	s_cselect_b32 s9, s1, s9
	s_cselect_b32 s8, s0, s39
	v_add_u32_e32 v0, s69, v156
	s_cselect_b32 s59, s35, s37
	s_cselect_b32 s58, s34, s36
	s_add_i32 s39, 0, 0x14000
	ds_read_b128 v[144:147], v0
	ds_read_b128 v[148:151], v0 offset:1024
	ds_read_b128 v[160:163], v0 offset:2048
	ds_read_b128 v[164:167], v0 offset:3072
	v_add_u32_e32 v0, s39, v156
	ds_read_b128 v[168:171], v0
	ds_read_b128 v[172:175], v0 offset:1024
	ds_read_b128 v[176:179], v0 offset:2048
	ds_read_b128 v[180:183], v0 offset:3072
	v_lshl_add_u64 v[218:219], s[6:7], 0, v[140:141]
	s_add_i32 m0, s50, 0xc000
	ds_read_b128 v[184:187], v158
	ds_read_b128 v[188:191], v158 offset:1024
	ds_read_b128 v[192:195], v158 offset:2048
	ds_read_b128 v[196:199], v158 offset:3072
	ds_read_b128 v[202:205], v158 offset:4096
	ds_read_b128 v[206:209], v158 offset:5120
	ds_read_b128 v[210:213], v158 offset:6144
	ds_read_b128 v[214:217], v158 offset:7168
	global_load_lds_dwordx4 v[218:219], off
	v_lshl_add_u64 v[218:219], s[6:7], 0, v[142:143]
	s_add_i32 m0, s50, 0xe000
	s_nop 0
	global_load_lds_dwordx4 v[218:219], off
	s_waitcnt vmcnt(8)
	s_waitcnt lgkmcnt(0)
	s_barrier
	s_setprio 1
	s_waitcnt lgkmcnt(0)
	v_mfma_f32_16x16x32_bf16 v[126:129], v[144:147], v[184:187], 0
	v_mfma_f32_16x16x32_bf16 v[122:125], v[160:163], v[184:187], 0
	v_mfma_f32_16x16x32_bf16 v[110:113], v[144:147], v[192:195], 0
	v_mfma_f32_16x16x32_bf16 v[106:109], v[160:163], v[192:195], 0
	v_mfma_f32_16x16x32_bf16 v[94:97], v[144:147], v[202:205], 0
	v_mfma_f32_16x16x32_bf16 v[90:93], v[160:163], v[202:205], 0
	v_mfma_f32_16x16x32_bf16 v[78:81], v[144:147], v[210:213], 0
	v_mfma_f32_16x16x32_bf16 v[74:77], v[160:163], v[210:213], 0
	v_mfma_f32_16x16x32_bf16 v[126:129], v[148:151], v[188:191], v[126:129]
	v_mfma_f32_16x16x32_bf16 v[122:125], v[164:167], v[188:191], v[122:125]
	v_mfma_f32_16x16x32_bf16 v[110:113], v[148:151], v[196:199], v[110:113]
	v_mfma_f32_16x16x32_bf16 v[106:109], v[164:167], v[196:199], v[106:109]
	v_mfma_f32_16x16x32_bf16 v[94:97], v[148:151], v[206:209], v[94:97]
	v_mfma_f32_16x16x32_bf16 v[90:93], v[164:167], v[206:209], v[90:93]
	v_mfma_f32_16x16x32_bf16 v[78:81], v[148:151], v[214:217], v[78:81]
	v_mfma_f32_16x16x32_bf16 v[74:77], v[164:167], v[214:217], v[74:77]
	s_setprio 0
	s_setprio 1
	v_mfma_f32_16x16x32_bf16 v[118:121], v[168:171], v[184:187], 0
	v_mfma_f32_16x16x32_bf16 v[114:117], v[176:179], v[184:187], 0
	v_mfma_f32_16x16x32_bf16 v[102:105], v[168:171], v[192:195], 0
	v_mfma_f32_16x16x32_bf16 v[98:101], v[176:179], v[192:195], 0
	v_mfma_f32_16x16x32_bf16 v[86:89], v[168:171], v[202:205], 0
	v_mfma_f32_16x16x32_bf16 v[82:85], v[176:179], v[202:205], 0
	v_mfma_f32_16x16x32_bf16 v[70:73], v[168:171], v[210:213], 0
	v_mfma_f32_16x16x32_bf16 v[66:69], v[176:179], v[210:213], 0
	v_mfma_f32_16x16x32_bf16 v[118:121], v[172:175], v[188:191], v[118:121]
	v_mfma_f32_16x16x32_bf16 v[114:117], v[180:183], v[188:191], v[114:117]
	v_mfma_f32_16x16x32_bf16 v[102:105], v[172:175], v[196:199], v[102:105]
	v_mfma_f32_16x16x32_bf16 v[98:101], v[180:183], v[196:199], v[98:101]
	v_mfma_f32_16x16x32_bf16 v[86:89], v[172:175], v[206:209], v[86:89]
	v_mfma_f32_16x16x32_bf16 v[82:85], v[180:183], v[206:209], v[82:85]
	v_mfma_f32_16x16x32_bf16 v[70:73], v[172:175], v[214:217], v[70:73]
	v_mfma_f32_16x16x32_bf16 v[66:69], v[180:183], v[214:217], v[66:69]
	s_setprio 0
	s_barrier
	s_add_i32 s69, s69, s49
	v_lshl_add_u64 v[218:219], s[58:59], 0, v[136:137]
	s_mov_b32 m0, s69
	ds_read_b128 v[184:187], v158 offset:16384
	ds_read_b128 v[188:191], v158 offset:17408
	ds_read_b128 v[192:195], v158 offset:18432
	ds_read_b128 v[196:199], v158 offset:19456
	ds_read_b128 v[202:205], v158 offset:20480
	ds_read_b128 v[206:209], v158 offset:21504
	ds_read_b128 v[210:213], v158 offset:22528
	ds_read_b128 v[214:217], v158 offset:23552
	global_load_lds_dwordx4 v[218:219], off
	s_add_i32 m0, s69, 0x2000
	v_lshl_add_u64 v[220:221], s[58:59], 0, v[132:133]
	s_add_u32 s58, s58, s47
	s_addc_u32 s59, s59, 0
	s_add_i32 s39, s39, s49
	global_load_lds_dwordx4 v[220:221], off
	v_lshl_add_u64 v[222:223], s[58:59], 0, v[136:137]
	s_mov_b32 m0, s39
	v_lshl_add_u64 v[224:225], s[58:59], 0, v[132:133]
	global_load_lds_dwordx4 v[222:223], off
	s_add_i32 m0, s39, 0x2000
	v_lshl_add_u64 v[226:227], s[8:9], 0, v[134:135]
	global_load_lds_dwordx4 v[224:225], off
	s_mov_b32 m0, s50
	v_lshl_add_u64 v[228:229], s[8:9], 0, v[130:131]
	global_load_lds_dwordx4 v[226:227], off
	s_mov_b32 m0, s51
	s_nop 0
	global_load_lds_dwordx4 v[228:229], off
	s_waitcnt vmcnt(8)
	s_waitcnt lgkmcnt(0)
	s_barrier
	s_setprio 1
	s_waitcnt lgkmcnt(0)
	v_mfma_f32_16x16x32_bf16 v[62:65], v[144:147], v[184:187], 0
	v_mfma_f32_16x16x32_bf16 v[58:61], v[160:163], v[184:187], 0
	v_mfma_f32_16x16x32_bf16 v[46:49], v[144:147], v[192:195], 0
	v_mfma_f32_16x16x32_bf16 v[42:45], v[160:163], v[192:195], 0
	v_mfma_f32_16x16x32_bf16 v[30:33], v[144:147], v[202:205], 0
	v_mfma_f32_16x16x32_bf16 v[26:29], v[160:163], v[202:205], 0
	v_mfma_f32_16x16x32_bf16 v[14:17], v[144:147], v[210:213], 0
	v_mfma_f32_16x16x32_bf16 v[10:13], v[160:163], v[210:213], 0
	v_mfma_f32_16x16x32_bf16 v[62:65], v[148:151], v[188:191], v[62:65]
	v_mfma_f32_16x16x32_bf16 v[58:61], v[164:167], v[188:191], v[58:61]
	v_mfma_f32_16x16x32_bf16 v[46:49], v[148:151], v[196:199], v[46:49]
	v_mfma_f32_16x16x32_bf16 v[42:45], v[164:167], v[196:199], v[42:45]
	v_mfma_f32_16x16x32_bf16 v[30:33], v[148:151], v[206:209], v[30:33]
	v_mfma_f32_16x16x32_bf16 v[26:29], v[164:167], v[206:209], v[26:29]
	v_mfma_f32_16x16x32_bf16 v[14:17], v[148:151], v[214:217], v[14:17]
	v_mfma_f32_16x16x32_bf16 v[10:13], v[164:167], v[214:217], v[10:13]
	s_setprio 0
	s_setprio 1
	v_mfma_f32_16x16x32_bf16 v[54:57], v[168:171], v[184:187], 0
	v_mfma_f32_16x16x32_bf16 v[50:53], v[176:179], v[184:187], 0
	v_mfma_f32_16x16x32_bf16 v[38:41], v[168:171], v[192:195], 0
	v_mfma_f32_16x16x32_bf16 v[34:37], v[176:179], v[192:195], 0
	v_mfma_f32_16x16x32_bf16 v[22:25], v[168:171], v[202:205], 0
	v_mfma_f32_16x16x32_bf16 v[18:21], v[176:179], v[202:205], 0
	v_mfma_f32_16x16x32_bf16 v[6:9], v[168:171], v[210:213], 0
	v_mfma_f32_16x16x32_bf16 v[2:5], v[176:179], v[210:213], 0
	v_mfma_f32_16x16x32_bf16 v[54:57], v[172:175], v[188:191], v[54:57]
	v_mfma_f32_16x16x32_bf16 v[50:53], v[180:183], v[188:191], v[50:53]
	v_mfma_f32_16x16x32_bf16 v[38:41], v[172:175], v[196:199], v[38:41]
	v_mfma_f32_16x16x32_bf16 v[34:37], v[180:183], v[196:199], v[34:37]
	v_mfma_f32_16x16x32_bf16 v[22:25], v[172:175], v[206:209], v[22:25]
	v_mfma_f32_16x16x32_bf16 v[18:21], v[180:183], v[206:209], v[18:21]
	v_mfma_f32_16x16x32_bf16 v[6:9], v[172:175], v[214:217], v[6:9]
	v_mfma_f32_16x16x32_bf16 v[2:5], v[180:183], v[214:217], v[2:5]
	s_setprio 0
	s_barrier
	s_add_i32 s39, 0, 0x18000
	v_add_u32_e32 v0, s39, v156
	s_add_i32 s58, 0, 0x1c000
	ds_read_b128 v[144:147], v0
	ds_read_b128 v[148:151], v0 offset:1024
	ds_read_b128 v[160:163], v0 offset:2048
	ds_read_b128 v[164:167], v0 offset:3072
	v_add_u32_e32 v0, s58, v156
	ds_read_b128 v[168:171], v0
	ds_read_b128 v[172:175], v0 offset:1024
	ds_read_b128 v[176:179], v0 offset:2048
	ds_read_b128 v[180:183], v0 offset:3072
	s_add_u32 s8, s8, s14
	s_addc_u32 s9, s9, 0
	s_mov_b32 m0, s52
	v_lshl_add_u64 v[230:231], s[8:9], 0, v[134:135]
	ds_read_b128 v[184:187], v158 offset:32768
	ds_read_b128 v[188:191], v158 offset:33792
	ds_read_b128 v[192:195], v158 offset:34816
	ds_read_b128 v[196:199], v158 offset:35840
	ds_read_b128 v[202:205], v158 offset:36864
	ds_read_b128 v[206:209], v158 offset:37888
	ds_read_b128 v[210:213], v158 offset:38912
	ds_read_b128 v[214:217], v158 offset:39936
	global_load_lds_dwordx4 v[230:231], off
	v_lshl_add_u64 v[230:231], s[8:9], 0, v[130:131]
	s_mov_b32 m0, s53
	s_nop 0
	global_load_lds_dwordx4 v[230:231], off
	s_waitcnt vmcnt(8)
	s_waitcnt lgkmcnt(0)
	s_barrier
	s_setprio 1
	s_waitcnt lgkmcnt(0)
	v_mfma_f32_16x16x32_bf16 v[126:129], v[144:147], v[184:187], v[126:129]
	v_mfma_f32_16x16x32_bf16 v[122:125], v[160:163], v[184:187], v[122:125]
	v_mfma_f32_16x16x32_bf16 v[110:113], v[144:147], v[192:195], v[110:113]
	v_mfma_f32_16x16x32_bf16 v[106:109], v[160:163], v[192:195], v[106:109]
	v_mfma_f32_16x16x32_bf16 v[94:97], v[144:147], v[202:205], v[94:97]
	v_mfma_f32_16x16x32_bf16 v[90:93], v[160:163], v[202:205], v[90:93]
	v_mfma_f32_16x16x32_bf16 v[78:81], v[144:147], v[210:213], v[78:81]
	v_mfma_f32_16x16x32_bf16 v[74:77], v[160:163], v[210:213], v[74:77]
	v_mfma_f32_16x16x32_bf16 v[126:129], v[148:151], v[188:191], v[126:129]
	v_mfma_f32_16x16x32_bf16 v[122:125], v[164:167], v[188:191], v[122:125]
	v_mfma_f32_16x16x32_bf16 v[110:113], v[148:151], v[196:199], v[110:113]
	v_mfma_f32_16x16x32_bf16 v[106:109], v[164:167], v[196:199], v[106:109]
	v_mfma_f32_16x16x32_bf16 v[94:97], v[148:151], v[206:209], v[94:97]
	v_mfma_f32_16x16x32_bf16 v[90:93], v[164:167], v[206:209], v[90:93]
	v_mfma_f32_16x16x32_bf16 v[78:81], v[148:151], v[214:217], v[78:81]
	v_mfma_f32_16x16x32_bf16 v[74:77], v[164:167], v[214:217], v[74:77]
	s_setprio 0
	s_setprio 1
	v_mfma_f32_16x16x32_bf16 v[118:121], v[168:171], v[184:187], v[118:121]
	v_mfma_f32_16x16x32_bf16 v[114:117], v[176:179], v[184:187], v[114:117]
	v_mfma_f32_16x16x32_bf16 v[102:105], v[168:171], v[192:195], v[102:105]
	v_mfma_f32_16x16x32_bf16 v[98:101], v[176:179], v[192:195], v[98:101]
	v_mfma_f32_16x16x32_bf16 v[86:89], v[168:171], v[202:205], v[86:89]
	v_mfma_f32_16x16x32_bf16 v[82:85], v[176:179], v[202:205], v[82:85]
	v_mfma_f32_16x16x32_bf16 v[70:73], v[168:171], v[210:213], v[70:73]
	v_mfma_f32_16x16x32_bf16 v[66:69], v[176:179], v[210:213], v[66:69]
	v_mfma_f32_16x16x32_bf16 v[118:121], v[172:175], v[188:191], v[118:121]
	v_mfma_f32_16x16x32_bf16 v[114:117], v[180:183], v[188:191], v[114:117]
	v_mfma_f32_16x16x32_bf16 v[102:105], v[172:175], v[196:199], v[102:105]
	v_mfma_f32_16x16x32_bf16 v[98:101], v[180:183], v[196:199], v[98:101]
	v_mfma_f32_16x16x32_bf16 v[86:89], v[172:175], v[206:209], v[86:89]
	v_mfma_f32_16x16x32_bf16 v[82:85], v[180:183], v[206:209], v[82:85]
	v_mfma_f32_16x16x32_bf16 v[70:73], v[172:175], v[214:217], v[70:73]
	v_mfma_f32_16x16x32_bf16 v[66:69], v[180:183], v[214:217], v[66:69]
	s_setprio 0
	s_barrier
	s_add_i32 s8, s39, s49
	v_lshl_add_u64 v[218:219], v[218:219], 0, s[16:17]
	s_mov_b32 m0, s8
	ds_read_b128 v[184:187], v158 offset:49152
	ds_read_b128 v[188:191], v158 offset:50176
	ds_read_b128 v[192:195], v158 offset:51200
	ds_read_b128 v[196:199], v158 offset:52224
	ds_read_b128 v[202:205], v158 offset:53248
	ds_read_b128 v[206:209], v158 offset:54272
	ds_read_b128 v[210:213], v158 offset:55296
	ds_read_b128 v[214:217], v158 offset:56320
	global_load_lds_dwordx4 v[218:219], off
	v_lshl_add_u64 v[218:219], v[220:221], 0, s[16:17]
	s_add_i32 m0, s8, 0x2000
	s_add_i32 s8, s58, s49
	global_load_lds_dwordx4 v[218:219], off
	v_lshl_add_u64 v[218:219], v[222:223], 0, s[16:17]
	s_mov_b32 m0, s8
	s_nop 0
	global_load_lds_dwordx4 v[218:219], off
	v_lshl_add_u64 v[218:219], v[224:225], 0, s[16:17]
	s_add_i32 m0, s8, 0x2000
	s_nop 0
	global_load_lds_dwordx4 v[218:219], off
	v_lshl_add_u64 v[218:219], v[226:227], 0, s[16:17]
	s_mov_b32 m0, s54
	s_nop 0
	global_load_lds_dwordx4 v[218:219], off
	v_lshl_add_u64 v[218:219], v[228:229], 0, s[16:17]
	s_mov_b32 m0, s55
	s_nop 0
	global_load_lds_dwordx4 v[218:219], off
	s_waitcnt vmcnt(8)
	s_waitcnt lgkmcnt(0)
	s_barrier
	s_setprio 1
	s_waitcnt lgkmcnt(0)
	v_mfma_f32_16x16x32_bf16 v[62:65], v[144:147], v[184:187], v[62:65]
	v_mfma_f32_16x16x32_bf16 v[58:61], v[160:163], v[184:187], v[58:61]
	v_mfma_f32_16x16x32_bf16 v[46:49], v[144:147], v[192:195], v[46:49]
	v_mfma_f32_16x16x32_bf16 v[42:45], v[160:163], v[192:195], v[42:45]
	v_mfma_f32_16x16x32_bf16 v[30:33], v[144:147], v[202:205], v[30:33]
	v_mfma_f32_16x16x32_bf16 v[26:29], v[160:163], v[202:205], v[26:29]
	v_mfma_f32_16x16x32_bf16 v[14:17], v[144:147], v[210:213], v[14:17]
	v_mfma_f32_16x16x32_bf16 v[10:13], v[160:163], v[210:213], v[10:13]
	v_mfma_f32_16x16x32_bf16 v[62:65], v[148:151], v[188:191], v[62:65]
	v_mfma_f32_16x16x32_bf16 v[58:61], v[164:167], v[188:191], v[58:61]
	v_mfma_f32_16x16x32_bf16 v[46:49], v[148:151], v[196:199], v[46:49]
	v_mfma_f32_16x16x32_bf16 v[42:45], v[164:167], v[196:199], v[42:45]
	v_mfma_f32_16x16x32_bf16 v[30:33], v[148:151], v[206:209], v[30:33]
	v_mfma_f32_16x16x32_bf16 v[26:29], v[164:167], v[206:209], v[26:29]
	v_mfma_f32_16x16x32_bf16 v[14:17], v[148:151], v[214:217], v[14:17]
	v_mfma_f32_16x16x32_bf16 v[10:13], v[164:167], v[214:217], v[10:13]
	s_setprio 0
	s_setprio 1
	v_mfma_f32_16x16x32_bf16 v[54:57], v[168:171], v[184:187], v[54:57]
	v_mfma_f32_16x16x32_bf16 v[50:53], v[176:179], v[184:187], v[50:53]
	v_mfma_f32_16x16x32_bf16 v[38:41], v[168:171], v[192:195], v[38:41]
	v_mfma_f32_16x16x32_bf16 v[34:37], v[176:179], v[192:195], v[34:37]
	v_mfma_f32_16x16x32_bf16 v[22:25], v[168:171], v[202:205], v[22:25]
	v_mfma_f32_16x16x32_bf16 v[18:21], v[176:179], v[202:205], v[18:21]
	v_mfma_f32_16x16x32_bf16 v[6:9], v[168:171], v[210:213], v[6:9]
	v_mfma_f32_16x16x32_bf16 v[2:5], v[176:179], v[210:213], v[2:5]
	v_mfma_f32_16x16x32_bf16 v[54:57], v[172:175], v[188:191], v[54:57]
	v_mfma_f32_16x16x32_bf16 v[50:53], v[180:183], v[188:191], v[50:53]
	v_mfma_f32_16x16x32_bf16 v[38:41], v[172:175], v[196:199], v[38:41]
	v_mfma_f32_16x16x32_bf16 v[34:37], v[180:183], v[196:199], v[34:37]
	v_mfma_f32_16x16x32_bf16 v[22:25], v[172:175], v[206:209], v[22:25]
	v_mfma_f32_16x16x32_bf16 v[18:21], v[180:183], v[206:209], v[18:21]
	v_mfma_f32_16x16x32_bf16 v[6:9], v[172:175], v[214:217], v[6:9]
	v_mfma_f32_16x16x32_bf16 v[2:5], v[180:183], v[214:217], v[2:5]
	s_setprio 0
	s_barrier
	s_add_u32 s6, s6, 0x100
	s_addc_u32 s7, s7, 0
	s_add_u32 s36, s36, 0x100
	s_addc_u32 s37, s37, 0
	s_cmp_ge_u32 s38, s56
	s_mov_b32 s8, s38
	s_cbranch_scc0 .LBB0_211
	s_branch .Lg1_after
